# W3: on top of MV2c: the tile-load wait (vmcnt(0)) moved down to its first consumer, just before the first staging ds_write (one P.V MFMA later)
# speedup vs baseline: 1.0065x; 1.0065x over previous
.LBB0_633:
	s_waitcnt lgkmcnt(0)
	s_barrier
	v_lshl_add_u32 v187, s53, 14, v173
	ds_read_b64_tr_b16 v[188:189], v187 offset:0
	ds_read_b64_tr_b16 v[190:191], v187 offset:0x800
	ds_read_b64_tr_b16 v[192:193], v187 offset:0x1000
	ds_read_b64_tr_b16 v[194:195], v187 offset:0x1800
	ds_read_b64_tr_b16 v[196:197], v187 offset:0x2000
	ds_read_b64_tr_b16 v[198:199], v187 offset:0x2800
	ds_read_b64_tr_b16 v[200:201], v187 offset:0x3000
	ds_read_b64_tr_b16 v[202:203], v187 offset:0x3800
	s_lshl_b32 s52, s49, 14
	v_add_u32_e32 v208, s52, v174
	ds_read_b128 v[68:71], v208 offset:0
	ds_read_b128 v[72:75], v208 offset:0x2000
	v_add_u32_e32 v209, s52, v175
	ds_read_b128 v[204:207], v209 offset:0
	ds_read_b128 v[216:219], v209 offset:0x2000
	v_add_u32_e32 v210, s52, v176
	ds_read_b128 v[220:223], v210 offset:0
	ds_read_b128 v[224:227], v210 offset:0x2000
	v_add_u32_e32 v211, s52, v177
	ds_read_b128 v[228:231], v211 offset:0
	ds_read_b128 v[232:235], v211 offset:0x2000
	s_waitcnt lgkmcnt(4)
	v_mfma_f32_32x32x16_bf16 v[84:99], v[68:71], v[128:131], 0
	v_mfma_f32_32x32x16_bf16 v[68:83], v[72:75], v[128:131], 0
	v_mfma_f32_32x32x16_bf16 v[84:99], v[204:207], v[124:127], v[84:99]
	v_mfma_f32_32x32x16_bf16 v[68:83], v[216:219], v[124:127], v[68:83]
	ds_read_b128 v[204:207], v208 offset:0x80
	ds_read_b128 v[216:219], v208 offset:0x2080
	ds_read_b128 v[236:239], v209 offset:0x80
	ds_read_b128 v[242:245], v209 offset:0x2080
	s_waitcnt lgkmcnt(4)
	v_mfma_f32_32x32x16_bf16 v[84:99], v[220:223], v[120:123], v[84:99]
	v_mfma_f32_32x32x16_bf16 v[68:83], v[224:227], v[120:123], v[68:83]
	v_mfma_f32_32x32x16_bf16 v[84:99], v[228:231], v[116:119], v[84:99]
	v_mfma_f32_32x32x16_bf16 v[68:83], v[232:235], v[116:119], v[68:83]
	ds_read_b128 v[220:223], v210 offset:0x80
	ds_read_b128 v[224:227], v210 offset:0x2080
	ds_read_b128 v[228:231], v211 offset:0x80
	ds_read_b128 v[232:235], v211 offset:0x2080
	s_waitcnt lgkmcnt(4)
	v_mfma_f32_32x32x16_bf16 v[84:99], v[204:207], v[112:115], v[84:99]
	v_mfma_f32_32x32x16_bf16 v[68:83], v[216:219], v[112:115], v[68:83]
	v_mfma_f32_32x32x16_bf16 v[84:99], v[236:239], v[108:111], v[84:99]
	v_mfma_f32_32x32x16_bf16 v[68:83], v[242:245], v[108:111], v[68:83]
	s_waitcnt lgkmcnt(0)
	v_mfma_f32_32x32x16_bf16 v[84:99], v[220:223], v[104:107], v[84:99]
	v_mfma_f32_32x32x16_bf16 v[68:83], v[224:227], v[104:107], v[68:83]
	v_mfma_f32_32x32x16_bf16 v[84:99], v[228:231], v[100:103], v[84:99]
	v_mfma_f32_32x32x16_bf16 v[68:83], v[232:235], v[100:103], v[68:83]
	ds_read_b64_tr_b16 v[204:205], v187 offset:0x200
	ds_read_b64_tr_b16 v[206:207], v187 offset:0xa00
	ds_read_b64_tr_b16 v[216:217], v187 offset:0x1200
	ds_read_b64_tr_b16 v[218:219], v187 offset:0x1a00
	ds_read_b64_tr_b16 v[220:221], v187 offset:0x2200
	ds_read_b64_tr_b16 v[222:223], v187 offset:0x2a00
	ds_read_b64_tr_b16 v[224:225], v187 offset:0x3200
	ds_read_b64_tr_b16 v[226:227], v187 offset:0x3a00
	s_waitcnt lgkmcnt(8)
	v_mfma_f32_32x32x16_bf16 v[4:19], v[148:151], v[188:191], v[4:19]
	s_lshl_b32 s19, s51, 14
	s_add_i32 s8, s19, 0
	v_add_u32_e32 v236, s8, v179
	v_mfma_f32_32x32x16_bf16 v[4:19], v[152:155], v[192:195], v[4:19]
	s_waitcnt vmcnt(0)
	ds_write_b128 v236, v[144:147]
	v_add_u32_e32 v236, s8, v178
	v_mfma_f32_32x32x16_bf16 v[4:19], v[156:159], v[196:199], v[4:19]
	ds_write_b128 v236, v[136:139]
	v_add_u32_e32 v236, s8, v180
	v_mfma_f32_32x32x16_bf16 v[4:19], v[160:163], v[200:203], v[4:19]
	ds_read_b64_tr_b16 v[188:189], v187 offset:0x400
	ds_read_b64_tr_b16 v[190:191], v187 offset:0xc00
	ds_read_b64_tr_b16 v[192:193], v187 offset:0x1400
	ds_read_b64_tr_b16 v[194:195], v187 offset:0x1c00
	ds_read_b64_tr_b16 v[196:197], v187 offset:0x2400
	ds_read_b64_tr_b16 v[198:199], v187 offset:0x2c00
	ds_read_b64_tr_b16 v[200:201], v187 offset:0x3400
	ds_read_b64_tr_b16 v[202:203], v187 offset:0x3c00
	s_waitcnt lgkmcnt(10)
	v_mfma_f32_32x32x16_bf16 v[52:67], v[148:151], v[204:207], v[52:67]
	ds_write_b128 v236, v[140:143] offset:49152
	v_add_u32_e32 v236, s8, v181
	v_mfma_f32_32x32x16_bf16 v[52:67], v[152:155], v[216:219], v[52:67]
	ds_write_b128 v236, v[132:135] offset:49152
	s_add_i32 s48, s48, 1
	v_mfma_f32_32x32x16_bf16 v[52:67], v[156:159], v[220:223], v[52:67]
	s_sub_i32 s8, s50, s47
	s_min_u32 s36, s50, s8
	s_lshl_b64 s[8:9], s[36:37], 10
	s_cmp_lt_u32 s50, s47
	s_cselect_b32 s16, s30, s20
	s_cselect_b32 s17, s31, s21
	v_mfma_f32_32x32x16_bf16 v[52:67], v[160:163], v[224:227], v[52:67]
	ds_read_b64_tr_b16 v[204:205], v187 offset:0x600
	ds_read_b64_tr_b16 v[206:207], v187 offset:0xe00
	ds_read_b64_tr_b16 v[216:217], v187 offset:0x1600
	ds_read_b64_tr_b16 v[218:219], v187 offset:0x1e00
	ds_read_b64_tr_b16 v[220:221], v187 offset:0x2600
	ds_read_b64_tr_b16 v[222:223], v187 offset:0x2e00
	ds_read_b64_tr_b16 v[224:225], v187 offset:0x3600
	ds_read_b64_tr_b16 v[226:227], v187 offset:0x3e00
	s_cselect_b32 s36, s42, s26
	s_cselect_b32 s54, s43, s27
	s_add_u32 s16, s16, s8
	s_addc_u32 s17, s17, s9
	s_add_u32 s8, s36, s8
	s_addc_u32 s9, s54, s9
	s_waitcnt lgkmcnt(0)
